# P1: the forget-projection weight slice is loaded before the weight transposes and stored to LDS after them (no two-round-trip staging loop between the two workgroup barriers)
# baseline (speedup 1.0000x reference)
; #define LAS __attribute__((address_space(3)))
; __device__ __forceinline__ void phase1(const Params& p, LAS unsigned char* lds, int tid, int lane, int wave) {
;     ...
;     if (gridDim.x == 256) {
;         if (blockIdx.x < 176) transposes(p, lds, NIT_IN + 2240, NIT_ALL, blockIdx.x * 8 + wave, 176 * 8, lane, wave);
;         else transposes(p, lds, NIT_IN, NIT_IN + 2240, (blockIdx.x - 176) * 8 + wave, 80 * 8, lane, wave);
;     } else transposes(p, lds, gridDim.x > 192 ? NIT_IN : 0, NIT_ALL, blockIdx.x * 8 + wave, gridDim.x * 8, lane, wave);
;     __syncthreads();
;     LAS float* wf = (LAS float*)lds;
;     for (int i = tid; i < 8192; i += 512) { const int k = i >> 3, h = i & 7; wf[h * 1024 + k] = p.w_in[(size_t)k * DIN + 1536 + h]; }
.LBB0_137:
	s_andn2_b64 vcc, exec, s[6:7]
	s_cbranch_vccnz .LBB0_184
	v_and_b32_e32 v152, 7, v208
	v_lshlrev_b32_e32 v152, 2, v152
	v_mul_u32_u24_e32 v153, 0x3020, v174
	v_add_u32_e32 v152, v152, v153
	v_add_u32_e32 v152, 0x1800, v152
	s_mov_b32 s52, s40
	s_mov_b32 s53, s41
	global_load_dword v176, v152, s[52:53]
	s_add_u32 s52, s52, 0xc0800
	s_addc_u32 s53, s53, 0
	global_load_dword v177, v152, s[52:53]
	s_add_u32 s52, s52, 0xc0800
	s_addc_u32 s53, s53, 0
	global_load_dword v178, v152, s[52:53]
	s_add_u32 s52, s52, 0xc0800
	s_addc_u32 s53, s53, 0
	global_load_dword v179, v152, s[52:53]
	s_add_u32 s52, s52, 0xc0800
	s_addc_u32 s53, s53, 0
	global_load_dword v180, v152, s[52:53]
	s_add_u32 s52, s52, 0xc0800
	s_addc_u32 s53, s53, 0
	global_load_dword v181, v152, s[52:53]
	s_add_u32 s52, s52, 0xc0800
	s_addc_u32 s53, s53, 0
	global_load_dword v182, v152, s[52:53]
	s_add_u32 s52, s52, 0xc0800
	s_addc_u32 s53, s53, 0
	global_load_dword v183, v152, s[52:53]
	s_add_u32 s52, s52, 0xc0800
	s_addc_u32 s53, s53, 0
	global_load_dword v184, v152, s[52:53]
	s_add_u32 s52, s52, 0xc0800
	s_addc_u32 s53, s53, 0
	global_load_dword v185, v152, s[52:53]
	s_add_u32 s52, s52, 0xc0800
	s_addc_u32 s53, s53, 0
	global_load_dword v186, v152, s[52:53]
	s_add_u32 s52, s52, 0xc0800
	s_addc_u32 s53, s53, 0
	global_load_dword v187, v152, s[52:53]
	s_add_u32 s52, s52, 0xc0800
	s_addc_u32 s53, s53, 0
	global_load_dword v188, v152, s[52:53]
	s_add_u32 s52, s52, 0xc0800
	s_addc_u32 s53, s53, 0
	global_load_dword v189, v152, s[52:53]
	s_add_u32 s52, s52, 0xc0800
	s_addc_u32 s53, s53, 0
	global_load_dword v190, v152, s[52:53]
	s_add_u32 s52, s52, 0xc0800
	s_addc_u32 s53, s53, 0
	global_load_dword v191, v152, s[52:53]
	v_and_b32_e32 v0, 31, v208
	v_lshlrev_b32_e32 v0, 2, v0
	v_lshrrev_b32_e32 v1, 5, v154
	v_lshrrev_b32_e32 v2, 3, v154
	v_and_b32_e32 v3, 7, v208
	v_mul_u32_u24_e32 v6, 0x420, v3
	v_lshlrev_b32_e32 v3, 4, v3
	s_mul_i32 s0, s58, 0x2200
	v_mul_u32_u24_e32 v4, 0x84, v1
	v_add3_u32 v7, s0, v0, v4
	v_add_u32_e32 v8, 0x400, v7
	v_add_u32_e32 v9, 0x800, v7
	v_add_u32_e32 v10, 0xc00, v7
	v_add_u32_e32 v11, 0x1000, v7
	v_add_u32_e32 v12, 0x1400, v7
	v_add_u32_e32 v13, 0x1800, v7
	v_add_u32_e32 v14, 0x1c00, v7
	v_lshlrev_b32_e32 v4, 2, v2
	v_add3_u32 v5, s0, v6, v4
	s_mov_b32 s8, s30
	s_and_b32 s9, s31, 0xffff
	s_brev_b32 s10, -2
	s_mov_b32 s11, 0x20000
	s_lshl_b32 s4, s2, 3
	s_add_i32 s4, s4, s58
	s_cmpk_gt_u32 s2, 0xaf
	s_cbranch_scc1 .Lp1_grpB
	s_addk_i32 s4, 0xec0
	s_cmpk_lt_u32 s4, 0x1300
	s_cbranch_scc1 .Lp1_n2
	s_branch .Lp1_n1

; #define LAS __attribute__((address_space(3)))
; __device__ __forceinline__ void phase1(const Params& p, LAS unsigned char* lds, int tid, int lane, int wave) {
;     ...
;     __syncthreads();
;     LAS float* wf = (LAS float*)lds;
;     for (int i = tid; i < 8192; i += 512) { const int k = i >> 3, h = i & 7; wf[h * 1024 + k] = p.w_in[(size_t)k * DIN + 1536 + h]; }
;     __syncthreads();
.Lwf_fast:
	v_and_b32_e32 v155, 7, v208
	v_lshlrev_b32_e32 v0, 12, v155
	v_lshl_add_u32 v0, v174, 2, v0
	s_waitcnt vmcnt(0)
	s_barrier
	ds_write_b32 v0, v176
	ds_write_b32 v0, v177 offset:256
	ds_write_b32 v0, v178 offset:512
	ds_write_b32 v0, v179 offset:768
	ds_write_b32 v0, v180 offset:1024
	ds_write_b32 v0, v181 offset:1280
	ds_write_b32 v0, v182 offset:1536
	ds_write_b32 v0, v183 offset:1792
	ds_write_b32 v0, v184 offset:2048
	ds_write_b32 v0, v185 offset:2304
	ds_write_b32 v0, v186 offset:2560
	ds_write_b32 v0, v187 offset:2816
	ds_write_b32 v0, v188 offset:3072
	ds_write_b32 v0, v189 offset:3328
	ds_write_b32 v0, v190 offset:3584
	ds_write_b32 v0, v191 offset:3840
	s_mov_b64 s[6:7], exec
	s_branch .LBB0_192
